# scan compute body: second nop-filling pass (712 -> 702 instructions per 32 steps)
# baseline (speedup 1.0000x reference)
; #define LAS __attribute__((address_space(3)))
; #define RW_LD(X, s) do { X.d = *(const LAS f32x4*)(bs + (s) * 256); X.k = *(const LAS f32x4*)(bs + 8192 + (s) * 256); X.a = *(const LAS f32x4*)(bs + 16384 + (s) * 256); \
;                          X.p = *(const LAS f32x4*)(bs + 24576 + (s) * 256); X.r = *(const LAS f32x4*)(bs + 32768 + (s) * 256); X.v = *(const LAS float*)(bv + (s) * 64); } while (0)
; #define RW_STEP(X, s) do { float sa = fmaf(S[3], X.k[3], fmaf(S[2], X.k[2], fmaf(S[1], X.k[1], S[0] * X.k[0]))); const f32x4 T = S * X.d + X.v * X.p; sa = -red16(sa); \
;                            S = T + sa * X.a; float y = fmaf(S[3], X.r[3], fmaf(S[2], X.r[2], fmaf(S[1], X.r[1], S[0] * X.r[0]))); y = red16(y); \
;                            yk = fmaf(selv[(s) & 15], y, yk); } while (0)
; #define RW_YST(s) do { if ((s) == 15) { ob[(size_t)(rowbase + c * 32 + seg) * D + 512 + h * 64 + vrow] = f2bf(yk); yk = 0.f; } } while (0)
; __device__ __forceinline__ void rwkv_scan(const Params& p, LAS unsigned char* lds, int rowbase, int T, int h, int q4, const float* S0, float* Sout) {
;     ...
;         __syncthreads();
;         if (c + 1 < nch) gload(c + 1);
;         if (comp) {
;             const LAS unsigned char* bs = b + seg * 16; const LAS unsigned char* bv = b + 40960 + vloc * 4;
;     ...
;             RwStep xa, xb, xc; float yk = 0.f;
;     ...
;             RW_LD(xa, 0); RW_LD(xb, 1);
; #pragma unroll
;             for (int s = 0; s < 30; s += 3) {
;                 RW_LD(xc, s + 2); RW_STEP(xa, s); RW_YST(s);
;                 RW_LD(xa, s + 3); RW_STEP(xb, s + 1); RW_YST(s + 1);
;                 RW_LD(xb, s + 4); RW_STEP(xc, s + 2); RW_YST(s + 2);
;             }
.Lrw3_cloop:
	s_barrier
	ds_read_b128 v[76:79], v2 offset:0
	ds_read_b128 v[84:87], v2 offset:16384
	ds_read_b128 v[80:83], v2 offset:8192
	ds_read_b128 v[124:127], v2 offset:24576
	ds_read_b128 v[24:27], v3 offset:0
	ds_read_b128 v[88:91], v2 offset:256
	ds_read_b128 v[96:99], v2 offset:16640
	ds_read_b128 v[92:95], v2 offset:8448
	ds_read_b128 v[128:131], v2 offset:24832
	ds_read_b128 v[100:103], v2 offset:512
	ds_read_b128 v[108:111], v2 offset:16896
	ds_read_b128 v[104:107], v2 offset:8704
	ds_read_b128 v[132:135], v2 offset:25088
	s_waitcnt lgkmcnt(5)
	v_pk_mul_f32 v[72:73], v[12:13], v[76:77]
	v_pk_fma_f32 v[72:73], v[14:15], v[78:79], v[72:73]
	ds_read_b128 v[112:115], v2 offset:768
	v_add_f32_e32 v74, v72, v73
	ds_read_b128 v[120:123], v2 offset:17152
	ds_read_b128 v[116:119], v2 offset:8960
	v_add_f32_dpp v74, v74, v74 quad_perm:[1,0,3,2] row_mask:0xf bank_mask:0xf bound_ctrl:1
	ds_read_b128 v[136:139], v2 offset:25344
	v_pk_fma_f32 v[16:17], v[24:25], v[84:85], v[12:13] op_sel_hi:[0,1,1]
	v_add_f32_dpp v74, v74, v74 quad_perm:[2,3,0,1] row_mask:0xf bank_mask:0xf bound_ctrl:1
	v_pk_fma_f32 v[18:19], v[24:25], v[86:87], v[14:15] op_sel_hi:[0,1,1]
	s_nop 0
	v_add_f32_dpp v74, v74, v74 row_half_mirror row_mask:0xf bank_mask:0xf bound_ctrl:1
	s_nop 1
	v_add_f32_dpp v74, v74, v74 row_mirror row_mask:0xf bank_mask:0xf bound_ctrl:1
	v_pk_fma_f32 v[12:13], v[80:81], v[74:75], v[16:17] op_sel_hi:[1,0,1] neg_lo:[0,1,0] neg_hi:[0,1,0]
	v_pk_fma_f32 v[14:15], v[82:83], v[74:75], v[18:19] op_sel_hi:[1,0,1] neg_lo:[0,1,0] neg_hi:[0,1,0]
	v_pk_mul_f32 v[72:73], v[12:13], v[88:89]
	v_pk_fma_f32 v[72:73], v[14:15], v[90:91], v[72:73]
	ds_read_b128 v[76:79], v2 offset:1024
	v_add_f32_e32 v74, v72, v73
	ds_read_b128 v[84:87], v2 offset:17408
	ds_read_b128 v[80:83], v2 offset:9216
	v_add_f32_dpp v74, v74, v74 quad_perm:[1,0,3,2] row_mask:0xf bank_mask:0xf bound_ctrl:1
	ds_read_b128 v[140:143], v2 offset:25600
	ds_read_b128 v[28:31], v3 offset:16
	v_add_f32_dpp v74, v74, v74 quad_perm:[2,3,0,1] row_mask:0xf bank_mask:0xf bound_ctrl:1
	v_pk_fma_f32 v[16:17], v[24:25], v[96:97], v[12:13] op_sel:[1,0,0] op_sel_hi:[1,1,1]
	v_pk_fma_f32 v[18:19], v[24:25], v[98:99], v[14:15] op_sel:[1,0,0] op_sel_hi:[1,1,1]
	v_add_f32_dpp v74, v74, v74 row_half_mirror row_mask:0xf bank_mask:0xf bound_ctrl:1
	v_pk_mul_f32 v[198:199], v[12:13], v[124:125]
	v_pk_fma_f32 v[198:199], v[14:15], v[126:127], v[198:199]
	v_add_f32_dpp v74, v74, v74 row_mirror row_mask:0xf bank_mask:0xf bound_ctrl:1
	v_add_f32_e32 v144, v198, v199
	v_pk_fma_f32 v[12:13], v[92:93], v[74:75], v[16:17] op_sel_hi:[1,0,1] neg_lo:[0,1,0] neg_hi:[0,1,0]
	v_pk_fma_f32 v[14:15], v[94:95], v[74:75], v[18:19] op_sel_hi:[1,0,1] neg_lo:[0,1,0] neg_hi:[0,1,0]
	s_waitcnt lgkmcnt(6)
	v_pk_mul_f32 v[72:73], v[12:13], v[100:101]
	v_pk_fma_f32 v[72:73], v[14:15], v[102:103], v[72:73]
	ds_read_b128 v[88:91], v2 offset:1280
	v_add_f32_e32 v74, v72, v73
	ds_read_b128 v[96:99], v2 offset:17664
	ds_read_b128 v[92:95], v2 offset:9472
	v_add_f32_dpp v74, v74, v74 quad_perm:[1,0,3,2] row_mask:0xf bank_mask:0xf bound_ctrl:1
	ds_read_b128 v[124:127], v2 offset:25856
	v_pk_fma_f32 v[16:17], v[26:27], v[108:109], v[12:13] op_sel_hi:[0,1,1]
	v_add_f32_dpp v74, v74, v74 quad_perm:[2,3,0,1] row_mask:0xf bank_mask:0xf bound_ctrl:1
	v_pk_fma_f32 v[18:19], v[26:27], v[110:111], v[14:15] op_sel_hi:[0,1,1]
	v_pk_mul_f32 v[198:199], v[12:13], v[128:129]
	v_add_f32_dpp v74, v74, v74 row_half_mirror row_mask:0xf bank_mask:0xf bound_ctrl:1
	v_pk_fma_f32 v[198:199], v[14:15], v[130:131], v[198:199]
	v_add_f32_e32 v145, v198, v199
	v_add_f32_dpp v74, v74, v74 row_mirror row_mask:0xf bank_mask:0xf bound_ctrl:1
	v_pk_fma_f32 v[12:13], v[104:105], v[74:75], v[16:17] op_sel_hi:[1,0,1] neg_lo:[0,1,0] neg_hi:[0,1,0]
	v_pk_fma_f32 v[14:15], v[106:107], v[74:75], v[18:19] op_sel_hi:[1,0,1] neg_lo:[0,1,0] neg_hi:[0,1,0]
	v_pk_mul_f32 v[72:73], v[12:13], v[112:113]
	v_pk_fma_f32 v[72:73], v[14:15], v[114:115], v[72:73]
	ds_read_b128 v[100:103], v2 offset:1536
	v_add_f32_e32 v74, v72, v73
	ds_read_b128 v[108:111], v2 offset:17920
	ds_read_b128 v[104:107], v2 offset:9728
	v_add_f32_dpp v74, v74, v74 quad_perm:[1,0,3,2] row_mask:0xf bank_mask:0xf bound_ctrl:1
	ds_read_b128 v[128:131], v2 offset:26112
	v_pk_fma_f32 v[16:17], v[26:27], v[120:121], v[12:13] op_sel:[1,0,0] op_sel_hi:[1,1,1]
	v_add_f32_dpp v74, v74, v74 quad_perm:[2,3,0,1] row_mask:0xf bank_mask:0xf bound_ctrl:1
	v_pk_fma_f32 v[18:19], v[26:27], v[122:123], v[14:15] op_sel:[1,0,0] op_sel_hi:[1,1,1]
	v_pk_mul_f32 v[198:199], v[12:13], v[132:133]
	v_add_f32_dpp v74, v74, v74 row_half_mirror row_mask:0xf bank_mask:0xf bound_ctrl:1
	v_pk_fma_f32 v[198:199], v[14:15], v[134:135], v[198:199]
	v_add_f32_e32 v146, v198, v199
	v_add_f32_dpp v74, v74, v74 row_mirror row_mask:0xf bank_mask:0xf bound_ctrl:1
	v_pk_fma_f32 v[12:13], v[116:117], v[74:75], v[16:17] op_sel_hi:[1,0,1] neg_lo:[0,1,0] neg_hi:[0,1,0]
	v_pk_fma_f32 v[14:15], v[118:119], v[74:75], v[18:19] op_sel_hi:[1,0,1] neg_lo:[0,1,0] neg_hi:[0,1,0]
	s_waitcnt lgkmcnt(5)
; #define RW_LD(X, s) do { X.d = *(const LAS f32x4*)(bs + (s) * 256); X.k = *(const LAS f32x4*)(bs + 8192 + (s) * 256); X.a = *(const LAS f32x4*)(bs + 16384 + (s) * 256); \
;                          X.p = *(const LAS f32x4*)(bs + 24576 + (s) * 256); X.r = *(const LAS f32x4*)(bs + 32768 + (s) * 256); X.v = *(const LAS float*)(bv + (s) * 64); } while (0)
; #define RW_STEP(X, s) do { float sa = fmaf(S[3], X.k[3], fmaf(S[2], X.k[2], fmaf(S[1], X.k[1], S[0] * X.k[0]))); const f32x4 T = S * X.d + X.v * X.p; sa = -red16(sa); \
;                            S = T + sa * X.a; float y = fmaf(S[3], X.r[3], fmaf(S[2], X.r[2], fmaf(S[1], X.r[1], S[0] * X.r[0]))); y = red16(y); \
;                            yk = fmaf(selv[(s) & 15], y, yk); } while (0)
; #define RW_YST(s) do { if ((s) == 15) { ob[(size_t)(rowbase + c * 32 + seg) * D + 512 + h * 64 + vrow] = f2bf(yk); yk = 0.f; } } while (0)
; __device__ __forceinline__ void rwkv_scan(const Params& p, LAS unsigned char* lds, int rowbase, int T, int h, int q4, const float* S0, float* Sout) {
;     ...
;             RwStep xa, xb, xc; float yk = 0.f;
;     ...
;             RW_LD(xa, 0); RW_LD(xb, 1);
; #pragma unroll
;             for (int s = 0; s < 30; s += 3) {
;                 RW_LD(xc, s + 2); RW_STEP(xa, s); RW_YST(s);
;                 RW_LD(xa, s + 3); RW_STEP(xb, s + 1); RW_YST(s + 1);
;                 RW_LD(xb, s + 4); RW_STEP(xc, s + 2); RW_YST(s + 2);
;             }
	v_pk_mul_f32 v[72:73], v[12:13], v[76:77]
	v_pk_fma_f32 v[72:73], v[14:15], v[78:79], v[72:73]
	ds_read_b128 v[112:115], v2 offset:1792
	v_add_f32_e32 v74, v72, v73
	ds_read_b128 v[120:123], v2 offset:18176
	ds_read_b128 v[116:119], v2 offset:9984
	v_add_f32_dpp v74, v74, v74 quad_perm:[1,0,3,2] row_mask:0xf bank_mask:0xf bound_ctrl:1
	ds_read_b128 v[132:135], v2 offset:26368
	v_pk_fma_f32 v[16:17], v[28:29], v[84:85], v[12:13] op_sel_hi:[0,1,1]
	v_add_f32_dpp v74, v74, v74 quad_perm:[2,3,0,1] row_mask:0xf bank_mask:0xf bound_ctrl:1
	v_pk_fma_f32 v[18:19], v[28:29], v[86:87], v[14:15] op_sel_hi:[0,1,1]
	v_pk_mul_f32 v[198:199], v[12:13], v[136:137]
	v_add_f32_dpp v74, v74, v74 row_half_mirror row_mask:0xf bank_mask:0xf bound_ctrl:1
	v_pk_fma_f32 v[198:199], v[14:15], v[138:139], v[198:199]
	v_add_f32_e32 v147, v198, v199
	v_add_f32_dpp v74, v74, v74 row_mirror row_mask:0xf bank_mask:0xf bound_ctrl:1
	v_pk_fma_f32 v[12:13], v[80:81], v[74:75], v[16:17] op_sel_hi:[1,0,1] neg_lo:[0,1,0] neg_hi:[0,1,0]
	v_pk_fma_f32 v[14:15], v[82:83], v[74:75], v[18:19] op_sel_hi:[1,0,1] neg_lo:[0,1,0] neg_hi:[0,1,0]
	v_pk_mul_f32 v[72:73], v[12:13], v[88:89]
	v_pk_fma_f32 v[72:73], v[14:15], v[90:91], v[72:73]
	ds_read_b128 v[76:79], v2 offset:2048
	v_add_f32_e32 v74, v72, v73
	ds_read_b128 v[84:87], v2 offset:18432
	ds_read_b128 v[80:83], v2 offset:10240
	v_add_f32_dpp v74, v74, v74 quad_perm:[1,0,3,2] row_mask:0xf bank_mask:0xf bound_ctrl:1
	ds_read_b128 v[136:139], v2 offset:26624
	ds_read_b128 v[24:27], v3 offset:32
	v_add_f32_dpp v74, v74, v74 quad_perm:[2,3,0,1] row_mask:0xf bank_mask:0xf bound_ctrl:1
	v_pk_fma_f32 v[16:17], v[28:29], v[96:97], v[12:13] op_sel:[1,0,0] op_sel_hi:[1,1,1]
	v_pk_fma_f32 v[18:19], v[28:29], v[98:99], v[14:15] op_sel:[1,0,0] op_sel_hi:[1,1,1]
	v_add_f32_dpp v74, v74, v74 row_half_mirror row_mask:0xf bank_mask:0xf bound_ctrl:1
	v_pk_mul_f32 v[198:199], v[12:13], v[140:141]
	v_pk_fma_f32 v[198:199], v[14:15], v[142:143], v[198:199]
	v_add_f32_dpp v74, v74, v74 row_mirror row_mask:0xf bank_mask:0xf bound_ctrl:1
	v_add_f32_e32 v148, v198, v199
	v_pk_fma_f32 v[12:13], v[92:93], v[74:75], v[16:17] op_sel_hi:[1,0,1] neg_lo:[0,1,0] neg_hi:[0,1,0]
	v_pk_fma_f32 v[14:15], v[94:95], v[74:75], v[18:19] op_sel_hi:[1,0,1] neg_lo:[0,1,0] neg_hi:[0,1,0]
	s_waitcnt lgkmcnt(6)
	v_pk_mul_f32 v[72:73], v[12:13], v[100:101]
	v_pk_fma_f32 v[72:73], v[14:15], v[102:103], v[72:73]
	ds_read_b128 v[88:91], v2 offset:2304
	v_add_f32_e32 v74, v72, v73
	ds_read_b128 v[96:99], v2 offset:18688
	ds_read_b128 v[92:95], v2 offset:10496
	v_add_f32_dpp v74, v74, v74 quad_perm:[1,0,3,2] row_mask:0xf bank_mask:0xf bound_ctrl:1
	ds_read_b128 v[140:143], v2 offset:26880
	v_pk_fma_f32 v[16:17], v[30:31], v[108:109], v[12:13] op_sel_hi:[0,1,1]
	v_add_f32_dpp v74, v74, v74 quad_perm:[2,3,0,1] row_mask:0xf bank_mask:0xf bound_ctrl:1
	v_pk_fma_f32 v[18:19], v[30:31], v[110:111], v[14:15] op_sel_hi:[0,1,1]
	v_pk_mul_f32 v[198:199], v[12:13], v[124:125]
	v_add_f32_dpp v74, v74, v74 row_half_mirror row_mask:0xf bank_mask:0xf bound_ctrl:1
	v_pk_fma_f32 v[198:199], v[14:15], v[126:127], v[198:199]
	v_add_f32_e32 v149, v198, v199
	v_add_f32_dpp v74, v74, v74 row_mirror row_mask:0xf bank_mask:0xf bound_ctrl:1
	v_pk_fma_f32 v[12:13], v[104:105], v[74:75], v[16:17] op_sel_hi:[1,0,1] neg_lo:[0,1,0] neg_hi:[0,1,0]
	v_pk_fma_f32 v[14:15], v[106:107], v[74:75], v[18:19] op_sel_hi:[1,0,1] neg_lo:[0,1,0] neg_hi:[0,1,0]
	v_pk_mul_f32 v[72:73], v[12:13], v[112:113]
	v_pk_fma_f32 v[72:73], v[14:15], v[114:115], v[72:73]
	ds_read_b128 v[100:103], v2 offset:2560
	v_add_f32_e32 v74, v72, v73
	ds_read_b128 v[108:111], v2 offset:18944
	ds_read_b128 v[104:107], v2 offset:10752
	v_add_f32_dpp v74, v74, v74 quad_perm:[1,0,3,2] row_mask:0xf bank_mask:0xf bound_ctrl:1
	ds_read_b128 v[124:127], v2 offset:27136
	v_pk_fma_f32 v[16:17], v[30:31], v[120:121], v[12:13] op_sel:[1,0,0] op_sel_hi:[1,1,1]
	v_add_f32_dpp v74, v74, v74 quad_perm:[2,3,0,1] row_mask:0xf bank_mask:0xf bound_ctrl:1
	v_pk_fma_f32 v[18:19], v[30:31], v[122:123], v[14:15] op_sel:[1,0,0] op_sel_hi:[1,1,1]
	v_pk_mul_f32 v[198:199], v[12:13], v[128:129]
	v_add_f32_dpp v74, v74, v74 row_half_mirror row_mask:0xf bank_mask:0xf bound_ctrl:1
	v_pk_fma_f32 v[198:199], v[14:15], v[130:131], v[198:199]
	v_add_f32_e32 v150, v198, v199
	v_add_f32_dpp v74, v74, v74 row_mirror row_mask:0xf bank_mask:0xf bound_ctrl:1
	v_pk_fma_f32 v[12:13], v[116:117], v[74:75], v[16:17] op_sel_hi:[1,0,1] neg_lo:[0,1,0] neg_hi:[0,1,0]
	v_pk_fma_f32 v[14:15], v[118:119], v[74:75], v[18:19] op_sel_hi:[1,0,1] neg_lo:[0,1,0] neg_hi:[0,1,0]
	s_waitcnt lgkmcnt(5)
; #define RW_LD(X, s) do { X.d = *(const LAS f32x4*)(bs + (s) * 256); X.k = *(const LAS f32x4*)(bs + 8192 + (s) * 256); X.a = *(const LAS f32x4*)(bs + 16384 + (s) * 256); \
;                          X.p = *(const LAS f32x4*)(bs + 24576 + (s) * 256); X.r = *(const LAS f32x4*)(bs + 32768 + (s) * 256); X.v = *(const LAS float*)(bv + (s) * 64); } while (0)
; #define RW_STEP(X, s) do { float sa = fmaf(S[3], X.k[3], fmaf(S[2], X.k[2], fmaf(S[1], X.k[1], S[0] * X.k[0]))); const f32x4 T = S * X.d + X.v * X.p; sa = -red16(sa); \
;                            S = T + sa * X.a; float y = fmaf(S[3], X.r[3], fmaf(S[2], X.r[2], fmaf(S[1], X.r[1], S[0] * X.r[0]))); y = red16(y); \
;                            yk = fmaf(selv[(s) & 15], y, yk); } while (0)
; #define RW_YST(s) do { if ((s) == 15) { ob[(size_t)(rowbase + c * 32 + seg) * D + 512 + h * 64 + vrow] = f2bf(yk); yk = 0.f; } } while (0)
; __device__ __forceinline__ void rwkv_scan(const Params& p, LAS unsigned char* lds, int rowbase, int T, int h, int q4, const float* S0, float* Sout) {
;     ...
;             RwStep xa, xb, xc; float yk = 0.f;
;     ...
;             RW_LD(xa, 0); RW_LD(xb, 1);
; #pragma unroll
;             for (int s = 0; s < 30; s += 3) {
;                 RW_LD(xc, s + 2); RW_STEP(xa, s); RW_YST(s);
;                 RW_LD(xa, s + 3); RW_STEP(xb, s + 1); RW_YST(s + 1);
;                 RW_LD(xb, s + 4); RW_STEP(xc, s + 2); RW_YST(s + 2);
;             }
	v_pk_mul_f32 v[72:73], v[12:13], v[76:77]
	v_pk_fma_f32 v[72:73], v[14:15], v[78:79], v[72:73]
	ds_read_b128 v[112:115], v2 offset:2816
	v_add_f32_e32 v74, v72, v73
	ds_read_b128 v[120:123], v2 offset:19200
	ds_read_b128 v[116:119], v2 offset:11008
	v_add_f32_dpp v74, v74, v74 quad_perm:[1,0,3,2] row_mask:0xf bank_mask:0xf bound_ctrl:1
	ds_read_b128 v[128:131], v2 offset:27392
	v_pk_fma_f32 v[16:17], v[24:25], v[84:85], v[12:13] op_sel_hi:[0,1,1]
	v_add_f32_dpp v74, v74, v74 quad_perm:[2,3,0,1] row_mask:0xf bank_mask:0xf bound_ctrl:1
	v_pk_fma_f32 v[18:19], v[24:25], v[86:87], v[14:15] op_sel_hi:[0,1,1]
	v_pk_mul_f32 v[198:199], v[12:13], v[132:133]
	v_add_f32_dpp v74, v74, v74 row_half_mirror row_mask:0xf bank_mask:0xf bound_ctrl:1
	v_pk_fma_f32 v[198:199], v[14:15], v[134:135], v[198:199]
	v_add_f32_e32 v151, v198, v199
	v_add_f32_dpp v74, v74, v74 row_mirror row_mask:0xf bank_mask:0xf bound_ctrl:1
	v_pk_fma_f32 v[12:13], v[80:81], v[74:75], v[16:17] op_sel_hi:[1,0,1] neg_lo:[0,1,0] neg_hi:[0,1,0]
	v_pk_fma_f32 v[14:15], v[82:83], v[74:75], v[18:19] op_sel_hi:[1,0,1] neg_lo:[0,1,0] neg_hi:[0,1,0]
	v_pk_mul_f32 v[72:73], v[12:13], v[88:89]
	v_pk_fma_f32 v[72:73], v[14:15], v[90:91], v[72:73]
	ds_read_b128 v[76:79], v2 offset:3072
	v_add_f32_e32 v74, v72, v73
	ds_read_b128 v[84:87], v2 offset:19456
	ds_read_b128 v[80:83], v2 offset:11264
	v_add_f32_dpp v74, v74, v74 quad_perm:[1,0,3,2] row_mask:0xf bank_mask:0xf bound_ctrl:1
	ds_read_b128 v[132:135], v2 offset:27648
	ds_read_b128 v[28:31], v3 offset:48
	v_add_f32_dpp v74, v74, v74 quad_perm:[2,3,0,1] row_mask:0xf bank_mask:0xf bound_ctrl:1
	v_pk_fma_f32 v[16:17], v[24:25], v[96:97], v[12:13] op_sel:[1,0,0] op_sel_hi:[1,1,1]
	v_pk_fma_f32 v[18:19], v[24:25], v[98:99], v[14:15] op_sel:[1,0,0] op_sel_hi:[1,1,1]
	v_add_f32_dpp v74, v74, v74 row_half_mirror row_mask:0xf bank_mask:0xf bound_ctrl:1
	v_pk_mul_f32 v[198:199], v[12:13], v[136:137]
	v_pk_fma_f32 v[198:199], v[14:15], v[138:139], v[198:199]
	v_add_f32_dpp v74, v74, v74 row_mirror row_mask:0xf bank_mask:0xf bound_ctrl:1
	v_add_f32_e32 v152, v198, v199
	v_pk_fma_f32 v[12:13], v[92:93], v[74:75], v[16:17] op_sel_hi:[1,0,1] neg_lo:[0,1,0] neg_hi:[0,1,0]
	v_pk_fma_f32 v[14:15], v[94:95], v[74:75], v[18:19] op_sel_hi:[1,0,1] neg_lo:[0,1,0] neg_hi:[0,1,0]
	v_add_f32_dpp v176, v144, v144 row_mirror row_mask:0xf bank_mask:0x3
	s_waitcnt lgkmcnt(6)
	v_pk_mul_f32 v[72:73], v[12:13], v[100:101]
	v_add_f32_dpp v176, v152, v152 row_mirror row_mask:0xf bank_mask:0xc
	v_pk_fma_f32 v[72:73], v[14:15], v[102:103], v[72:73]
	ds_read_b128 v[88:91], v2 offset:3328
	v_add_f32_e32 v74, v72, v73
	ds_read_b128 v[96:99], v2 offset:19712
	ds_read_b128 v[92:95], v2 offset:11520
	v_add_f32_dpp v74, v74, v74 quad_perm:[1,0,3,2] row_mask:0xf bank_mask:0xf bound_ctrl:1
	ds_read_b128 v[136:139], v2 offset:27904
	v_pk_fma_f32 v[16:17], v[26:27], v[108:109], v[12:13] op_sel_hi:[0,1,1]
	v_add_f32_dpp v74, v74, v74 quad_perm:[2,3,0,1] row_mask:0xf bank_mask:0xf bound_ctrl:1
	v_pk_fma_f32 v[18:19], v[26:27], v[110:111], v[14:15] op_sel_hi:[0,1,1]
	v_pk_mul_f32 v[198:199], v[12:13], v[140:141]
	v_add_f32_dpp v74, v74, v74 row_half_mirror row_mask:0xf bank_mask:0xf bound_ctrl:1
	v_pk_fma_f32 v[198:199], v[14:15], v[142:143], v[198:199]
	v_add_f32_e32 v153, v198, v199
	v_add_f32_dpp v74, v74, v74 row_mirror row_mask:0xf bank_mask:0xf bound_ctrl:1
	v_pk_fma_f32 v[12:13], v[104:105], v[74:75], v[16:17] op_sel_hi:[1,0,1] neg_lo:[0,1,0] neg_hi:[0,1,0]
	v_pk_fma_f32 v[14:15], v[106:107], v[74:75], v[18:19] op_sel_hi:[1,0,1] neg_lo:[0,1,0] neg_hi:[0,1,0]
	v_add_f32_dpp v177, v145, v145 row_mirror row_mask:0xf bank_mask:0x3
	v_pk_mul_f32 v[72:73], v[12:13], v[112:113]
	v_pk_fma_f32 v[72:73], v[14:15], v[114:115], v[72:73]
	v_add_f32_dpp v177, v153, v153 row_mirror row_mask:0xf bank_mask:0xc
	ds_read_b128 v[100:103], v2 offset:3584
	v_add_f32_e32 v74, v72, v73
	ds_read_b128 v[108:111], v2 offset:19968
	ds_read_b128 v[104:107], v2 offset:11776
	v_add_f32_dpp v74, v74, v74 quad_perm:[1,0,3,2] row_mask:0xf bank_mask:0xf bound_ctrl:1
	ds_read_b128 v[140:143], v2 offset:28160
	v_pk_fma_f32 v[16:17], v[26:27], v[120:121], v[12:13] op_sel:[1,0,0] op_sel_hi:[1,1,1]
	v_add_f32_dpp v74, v74, v74 quad_perm:[2,3,0,1] row_mask:0xf bank_mask:0xf bound_ctrl:1
	v_pk_fma_f32 v[18:19], v[26:27], v[122:123], v[14:15] op_sel:[1,0,0] op_sel_hi:[1,1,1]
	v_pk_mul_f32 v[198:199], v[12:13], v[124:125]
	v_add_f32_dpp v74, v74, v74 row_half_mirror row_mask:0xf bank_mask:0xf bound_ctrl:1
	v_pk_fma_f32 v[198:199], v[14:15], v[126:127], v[198:199]
	v_add_f32_e32 v154, v198, v199
	v_add_f32_dpp v74, v74, v74 row_mirror row_mask:0xf bank_mask:0xf bound_ctrl:1
	v_pk_fma_f32 v[12:13], v[116:117], v[74:75], v[16:17] op_sel_hi:[1,0,1] neg_lo:[0,1,0] neg_hi:[0,1,0]
	v_pk_fma_f32 v[14:15], v[118:119], v[74:75], v[18:19] op_sel_hi:[1,0,1] neg_lo:[0,1,0] neg_hi:[0,1,0]
	v_add_f32_dpp v178, v146, v146 row_mirror row_mask:0xf bank_mask:0x3
	s_waitcnt lgkmcnt(5)
; #define RW_LD(X, s) do { X.d = *(const LAS f32x4*)(bs + (s) * 256); X.k = *(const LAS f32x4*)(bs + 8192 + (s) * 256); X.a = *(const LAS f32x4*)(bs + 16384 + (s) * 256); \
;                          X.p = *(const LAS f32x4*)(bs + 24576 + (s) * 256); X.r = *(const LAS f32x4*)(bs + 32768 + (s) * 256); X.v = *(const LAS float*)(bv + (s) * 64); } while (0)
; #define RW_STEP(X, s) do { float sa = fmaf(S[3], X.k[3], fmaf(S[2], X.k[2], fmaf(S[1], X.k[1], S[0] * X.k[0]))); const f32x4 T = S * X.d + X.v * X.p; sa = -red16(sa); \
;                            S = T + sa * X.a; float y = fmaf(S[3], X.r[3], fmaf(S[2], X.r[2], fmaf(S[1], X.r[1], S[0] * X.r[0]))); y = red16(y); \
;                            yk = fmaf(selv[(s) & 15], y, yk); } while (0)
; #define RW_YST(s) do { if ((s) == 15) { ob[(size_t)(rowbase + c * 32 + seg) * D + 512 + h * 64 + vrow] = f2bf(yk); yk = 0.f; } } while (0)
; __device__ __forceinline__ void rwkv_scan(const Params& p, LAS unsigned char* lds, int rowbase, int T, int h, int q4, const float* S0, float* Sout) {
;     ...
;             RwStep xa, xb, xc; float yk = 0.f;
;     ...
;             RW_LD(xa, 0); RW_LD(xb, 1);
; #pragma unroll
;             for (int s = 0; s < 30; s += 3) {
;                 RW_LD(xc, s + 2); RW_STEP(xa, s); RW_YST(s);
;                 RW_LD(xa, s + 3); RW_STEP(xb, s + 1); RW_YST(s + 1);
;                 RW_LD(xb, s + 4); RW_STEP(xc, s + 2); RW_YST(s + 2);
;             }
	v_pk_mul_f32 v[72:73], v[12:13], v[76:77]
	v_add_f32_dpp v178, v154, v154 row_mirror row_mask:0xf bank_mask:0xc
	v_pk_fma_f32 v[72:73], v[14:15], v[78:79], v[72:73]
	ds_read_b128 v[112:115], v2 offset:3840
	v_add_f32_e32 v74, v72, v73
	ds_read_b128 v[120:123], v2 offset:20224
	ds_read_b128 v[116:119], v2 offset:12032
	v_add_f32_dpp v74, v74, v74 quad_perm:[1,0,3,2] row_mask:0xf bank_mask:0xf bound_ctrl:1
	ds_read_b128 v[124:127], v2 offset:28416
	v_pk_fma_f32 v[16:17], v[28:29], v[84:85], v[12:13] op_sel_hi:[0,1,1]
	v_add_f32_dpp v74, v74, v74 quad_perm:[2,3,0,1] row_mask:0xf bank_mask:0xf bound_ctrl:1
	v_pk_fma_f32 v[18:19], v[28:29], v[86:87], v[14:15] op_sel_hi:[0,1,1]
	v_pk_mul_f32 v[198:199], v[12:13], v[128:129]
	v_add_f32_dpp v74, v74, v74 row_half_mirror row_mask:0xf bank_mask:0xf bound_ctrl:1
	v_pk_fma_f32 v[198:199], v[14:15], v[130:131], v[198:199]
	v_add_f32_e32 v155, v198, v199
	v_add_f32_dpp v74, v74, v74 row_mirror row_mask:0xf bank_mask:0xf bound_ctrl:1
	v_pk_fma_f32 v[12:13], v[80:81], v[74:75], v[16:17] op_sel_hi:[1,0,1] neg_lo:[0,1,0] neg_hi:[0,1,0]
	v_pk_fma_f32 v[14:15], v[82:83], v[74:75], v[18:19] op_sel_hi:[1,0,1] neg_lo:[0,1,0] neg_hi:[0,1,0]
	v_add_f32_dpp v179, v147, v147 row_mirror row_mask:0xf bank_mask:0x3
	v_pk_mul_f32 v[72:73], v[12:13], v[88:89]
	v_pk_fma_f32 v[72:73], v[14:15], v[90:91], v[72:73]
	v_add_f32_dpp v179, v155, v155 row_mirror row_mask:0xf bank_mask:0xc
	ds_read_b128 v[76:79], v2 offset:4096
	v_add_f32_e32 v74, v72, v73
	ds_read_b128 v[84:87], v2 offset:20480
	ds_read_b128 v[80:83], v2 offset:12288
	v_add_f32_dpp v74, v74, v74 quad_perm:[1,0,3,2] row_mask:0xf bank_mask:0xf bound_ctrl:1
	ds_read_b128 v[128:131], v2 offset:28672
	ds_read_b128 v[24:27], v3 offset:64
	v_add_f32_dpp v74, v74, v74 quad_perm:[2,3,0,1] row_mask:0xf bank_mask:0xf bound_ctrl:1
	v_pk_fma_f32 v[16:17], v[28:29], v[96:97], v[12:13] op_sel:[1,0,0] op_sel_hi:[1,1,1]
	v_pk_fma_f32 v[18:19], v[28:29], v[98:99], v[14:15] op_sel:[1,0,0] op_sel_hi:[1,1,1]
	v_add_f32_dpp v74, v74, v74 row_half_mirror row_mask:0xf bank_mask:0xf bound_ctrl:1
	v_pk_mul_f32 v[198:199], v[12:13], v[132:133]
	v_pk_fma_f32 v[198:199], v[14:15], v[134:135], v[198:199]
	v_add_f32_dpp v74, v74, v74 row_mirror row_mask:0xf bank_mask:0xf bound_ctrl:1
	v_add_f32_e32 v156, v198, v199
	v_pk_fma_f32 v[12:13], v[92:93], v[74:75], v[16:17] op_sel_hi:[1,0,1] neg_lo:[0,1,0] neg_hi:[0,1,0]
	v_pk_fma_f32 v[14:15], v[94:95], v[74:75], v[18:19] op_sel_hi:[1,0,1] neg_lo:[0,1,0] neg_hi:[0,1,0]
	v_add_f32_dpp v180, v148, v148 row_mirror row_mask:0xf bank_mask:0x3
	s_waitcnt lgkmcnt(6)
	v_pk_mul_f32 v[72:73], v[12:13], v[100:101]
	v_add_f32_dpp v180, v156, v156 row_mirror row_mask:0xf bank_mask:0xc
	v_pk_fma_f32 v[72:73], v[14:15], v[102:103], v[72:73]
	ds_read_b128 v[88:91], v2 offset:4352
	v_add_f32_e32 v74, v72, v73
	ds_read_b128 v[96:99], v2 offset:20736
	ds_read_b128 v[92:95], v2 offset:12544
	v_add_f32_dpp v74, v74, v74 quad_perm:[1,0,3,2] row_mask:0xf bank_mask:0xf bound_ctrl:1
	ds_read_b128 v[132:135], v2 offset:28928
	v_pk_fma_f32 v[16:17], v[30:31], v[108:109], v[12:13] op_sel_hi:[0,1,1]
	v_add_f32_dpp v74, v74, v74 quad_perm:[2,3,0,1] row_mask:0xf bank_mask:0xf bound_ctrl:1
	v_pk_fma_f32 v[18:19], v[30:31], v[110:111], v[14:15] op_sel_hi:[0,1,1]
	v_pk_mul_f32 v[198:199], v[12:13], v[136:137]
	v_add_f32_dpp v74, v74, v74 row_half_mirror row_mask:0xf bank_mask:0xf bound_ctrl:1
	v_pk_fma_f32 v[198:199], v[14:15], v[138:139], v[198:199]
	v_add_f32_e32 v157, v198, v199
	v_add_f32_dpp v74, v74, v74 row_mirror row_mask:0xf bank_mask:0xf bound_ctrl:1
	v_pk_fma_f32 v[12:13], v[104:105], v[74:75], v[16:17] op_sel_hi:[1,0,1] neg_lo:[0,1,0] neg_hi:[0,1,0]
	v_pk_fma_f32 v[14:15], v[106:107], v[74:75], v[18:19] op_sel_hi:[1,0,1] neg_lo:[0,1,0] neg_hi:[0,1,0]
	v_add_f32_dpp v184, v176, v176 row_half_mirror row_mask:0xf bank_mask:0x5
	v_pk_mul_f32 v[72:73], v[12:13], v[112:113]
	v_pk_fma_f32 v[72:73], v[14:15], v[114:115], v[72:73]
	v_add_f32_dpp v184, v180, v180 row_half_mirror row_mask:0xf bank_mask:0xa
	ds_read_b128 v[100:103], v2 offset:4608
	v_add_f32_e32 v74, v72, v73
	ds_read_b128 v[108:111], v2 offset:20992
	ds_read_b128 v[104:107], v2 offset:12800
	v_add_f32_dpp v74, v74, v74 quad_perm:[1,0,3,2] row_mask:0xf bank_mask:0xf bound_ctrl:1
	ds_read_b128 v[136:139], v2 offset:29184
	v_pk_fma_f32 v[16:17], v[30:31], v[120:121], v[12:13] op_sel:[1,0,0] op_sel_hi:[1,1,1]
	v_add_f32_dpp v74, v74, v74 quad_perm:[2,3,0,1] row_mask:0xf bank_mask:0xf bound_ctrl:1
	v_pk_fma_f32 v[18:19], v[30:31], v[122:123], v[14:15] op_sel:[1,0,0] op_sel_hi:[1,1,1]
	v_pk_mul_f32 v[198:199], v[12:13], v[140:141]
	v_add_f32_dpp v74, v74, v74 row_half_mirror row_mask:0xf bank_mask:0xf bound_ctrl:1
	v_pk_fma_f32 v[198:199], v[14:15], v[142:143], v[198:199]
	v_add_f32_e32 v158, v198, v199
	v_add_f32_dpp v74, v74, v74 row_mirror row_mask:0xf bank_mask:0xf bound_ctrl:1
	v_pk_fma_f32 v[12:13], v[116:117], v[74:75], v[16:17] op_sel_hi:[1,0,1] neg_lo:[0,1,0] neg_hi:[0,1,0]
	v_pk_fma_f32 v[14:15], v[118:119], v[74:75], v[18:19] op_sel_hi:[1,0,1] neg_lo:[0,1,0] neg_hi:[0,1,0]
	v_add_f32_dpp v181, v149, v149 row_mirror row_mask:0xf bank_mask:0x3
	v_add_f32_dpp v185, v177, v177 row_half_mirror row_mask:0xf bank_mask:0x5
	s_waitcnt lgkmcnt(5)
; #define RW_LD(X, s) do { X.d = *(const LAS f32x4*)(bs + (s) * 256); X.k = *(const LAS f32x4*)(bs + 8192 + (s) * 256); X.a = *(const LAS f32x4*)(bs + 16384 + (s) * 256); \
;                          X.p = *(const LAS f32x4*)(bs + 24576 + (s) * 256); X.r = *(const LAS f32x4*)(bs + 32768 + (s) * 256); X.v = *(const LAS float*)(bv + (s) * 64); } while (0)
; #define RW_STEP(X, s) do { float sa = fmaf(S[3], X.k[3], fmaf(S[2], X.k[2], fmaf(S[1], X.k[1], S[0] * X.k[0]))); const f32x4 T = S * X.d + X.v * X.p; sa = -red16(sa); \
;                            S = T + sa * X.a; float y = fmaf(S[3], X.r[3], fmaf(S[2], X.r[2], fmaf(S[1], X.r[1], S[0] * X.r[0]))); y = red16(y); \
;                            yk = fmaf(selv[(s) & 15], y, yk); } while (0)
; #define RW_YST(s) do { if ((s) == 15) { ob[(size_t)(rowbase + c * 32 + seg) * D + 512 + h * 64 + vrow] = f2bf(yk); yk = 0.f; } } while (0)
; __device__ __forceinline__ void rwkv_scan(const Params& p, LAS unsigned char* lds, int rowbase, int T, int h, int q4, const float* S0, float* Sout) {
;     ...
;             RwStep xa, xb, xc; float yk = 0.f;
;     ...
;             RW_LD(xa, 0); RW_LD(xb, 1);
; #pragma unroll
;             for (int s = 0; s < 30; s += 3) {
;                 RW_LD(xc, s + 2); RW_STEP(xa, s); RW_YST(s);
;                 RW_LD(xa, s + 3); RW_STEP(xb, s + 1); RW_YST(s + 1);
;                 RW_LD(xb, s + 4); RW_STEP(xc, s + 2); RW_YST(s + 2);
;             }
	v_add_f32_dpp v181, v157, v157 row_mirror row_mask:0xf bank_mask:0xc
	v_pk_mul_f32 v[72:73], v[12:13], v[76:77]
	v_pk_fma_f32 v[72:73], v[14:15], v[78:79], v[72:73]
	ds_read_b128 v[112:115], v2 offset:4864
	v_add_f32_e32 v74, v72, v73
	ds_read_b128 v[120:123], v2 offset:21248
	ds_read_b128 v[116:119], v2 offset:13056
	v_add_f32_dpp v74, v74, v74 quad_perm:[1,0,3,2] row_mask:0xf bank_mask:0xf bound_ctrl:1
	ds_read_b128 v[140:143], v2 offset:29440
	v_pk_fma_f32 v[16:17], v[24:25], v[84:85], v[12:13] op_sel_hi:[0,1,1]
	v_add_f32_dpp v74, v74, v74 quad_perm:[2,3,0,1] row_mask:0xf bank_mask:0xf bound_ctrl:1
	v_pk_fma_f32 v[18:19], v[24:25], v[86:87], v[14:15] op_sel_hi:[0,1,1]
	v_pk_mul_f32 v[198:199], v[12:13], v[124:125]
	v_add_f32_dpp v74, v74, v74 row_half_mirror row_mask:0xf bank_mask:0xf bound_ctrl:1
	v_pk_fma_f32 v[198:199], v[14:15], v[126:127], v[198:199]
	v_add_f32_e32 v159, v198, v199
	v_add_f32_dpp v74, v74, v74 row_mirror row_mask:0xf bank_mask:0xf bound_ctrl:1
	v_pk_fma_f32 v[12:13], v[80:81], v[74:75], v[16:17] op_sel_hi:[1,0,1] neg_lo:[0,1,0] neg_hi:[0,1,0]
	v_pk_fma_f32 v[14:15], v[82:83], v[74:75], v[18:19] op_sel_hi:[1,0,1] neg_lo:[0,1,0] neg_hi:[0,1,0]
	v_add_f32_dpp v185, v181, v181 row_half_mirror row_mask:0xf bank_mask:0xa
	v_add_f32_dpp v182, v150, v150 row_mirror row_mask:0xf bank_mask:0x3
	v_pk_mul_f32 v[72:73], v[12:13], v[88:89]
	v_pk_fma_f32 v[72:73], v[14:15], v[90:91], v[72:73]
	v_add_f32_dpp v182, v158, v158 row_mirror row_mask:0xf bank_mask:0xc
	ds_read_b128 v[76:79], v2 offset:5120
	v_add_f32_e32 v74, v72, v73
	ds_read_b128 v[84:87], v2 offset:21504
	ds_read_b128 v[80:83], v2 offset:13312
	v_add_f32_dpp v74, v74, v74 quad_perm:[1,0,3,2] row_mask:0xf bank_mask:0xf bound_ctrl:1
	ds_read_b128 v[124:127], v2 offset:29696
	ds_read_b128 v[28:31], v3 offset:80
	v_add_f32_dpp v74, v74, v74 quad_perm:[2,3,0,1] row_mask:0xf bank_mask:0xf bound_ctrl:1
	v_pk_fma_f32 v[16:17], v[24:25], v[96:97], v[12:13] op_sel:[1,0,0] op_sel_hi:[1,1,1]
	v_pk_fma_f32 v[18:19], v[24:25], v[98:99], v[14:15] op_sel:[1,0,0] op_sel_hi:[1,1,1]
	v_add_f32_dpp v74, v74, v74 row_half_mirror row_mask:0xf bank_mask:0xf bound_ctrl:1
	v_pk_mul_f32 v[198:199], v[12:13], v[128:129]
	v_pk_fma_f32 v[198:199], v[14:15], v[130:131], v[198:199]
	v_add_f32_dpp v74, v74, v74 row_mirror row_mask:0xf bank_mask:0xf bound_ctrl:1
	v_add_f32_e32 v160, v198, v199
	v_pk_fma_f32 v[12:13], v[92:93], v[74:75], v[16:17] op_sel_hi:[1,0,1] neg_lo:[0,1,0] neg_hi:[0,1,0]
	v_pk_fma_f32 v[14:15], v[94:95], v[74:75], v[18:19] op_sel_hi:[1,0,1] neg_lo:[0,1,0] neg_hi:[0,1,0]
	v_add_f32_dpp v186, v178, v178 row_half_mirror row_mask:0xf bank_mask:0x5
	s_nop 1
	v_add_f32_dpp v186, v182, v182 row_half_mirror row_mask:0xf bank_mask:0xa
	v_cndmask_b32_e64 v190, v184, v186, s[98:99]
	s_waitcnt lgkmcnt(6)
	v_pk_mul_f32 v[72:73], v[12:13], v[100:101]
	v_pk_fma_f32 v[72:73], v[14:15], v[102:103], v[72:73]
	ds_read_b128 v[88:91], v2 offset:5376
	v_add_f32_e32 v74, v72, v73
	ds_read_b128 v[96:99], v2 offset:21760
	ds_read_b128 v[92:95], v2 offset:13568
	v_add_f32_dpp v74, v74, v74 quad_perm:[1,0,3,2] row_mask:0xf bank_mask:0xf bound_ctrl:1
	ds_read_b128 v[128:131], v2 offset:29952
	v_pk_fma_f32 v[16:17], v[26:27], v[108:109], v[12:13] op_sel_hi:[0,1,1]
	v_add_f32_dpp v74, v74, v74 quad_perm:[2,3,0,1] row_mask:0xf bank_mask:0xf bound_ctrl:1
	v_pk_fma_f32 v[18:19], v[26:27], v[110:111], v[14:15] op_sel_hi:[0,1,1]
	v_pk_mul_f32 v[198:199], v[12:13], v[132:133]
	v_add_f32_dpp v74, v74, v74 row_half_mirror row_mask:0xf bank_mask:0xf bound_ctrl:1
	v_pk_fma_f32 v[198:199], v[14:15], v[134:135], v[198:199]
	v_add_f32_e32 v161, v198, v199
	v_add_f32_dpp v74, v74, v74 row_mirror row_mask:0xf bank_mask:0xf bound_ctrl:1
	v_pk_fma_f32 v[12:13], v[104:105], v[74:75], v[16:17] op_sel_hi:[1,0,1] neg_lo:[0,1,0] neg_hi:[0,1,0]
	v_pk_fma_f32 v[14:15], v[106:107], v[74:75], v[18:19] op_sel_hi:[1,0,1] neg_lo:[0,1,0] neg_hi:[0,1,0]
	v_cndmask_b32_e64 v191, v186, v184, s[98:99]
	v_add_f32_dpp v183, v151, v151 row_mirror row_mask:0xf bank_mask:0x3
	v_pk_mul_f32 v[72:73], v[12:13], v[112:113]
	v_add_f32_dpp v188, v191, v190 quad_perm:[2,3,0,1] row_mask:0xf bank_mask:0xf
	v_pk_fma_f32 v[72:73], v[14:15], v[114:115], v[72:73]
	ds_read_b128 v[100:103], v2 offset:5632
	v_add_f32_e32 v74, v72, v73
	ds_read_b128 v[108:111], v2 offset:22016
	ds_read_b128 v[104:107], v2 offset:13824
	v_add_f32_dpp v74, v74, v74 quad_perm:[1,0,3,2] row_mask:0xf bank_mask:0xf bound_ctrl:1
	ds_read_b128 v[132:135], v2 offset:30208
	v_pk_fma_f32 v[16:17], v[26:27], v[120:121], v[12:13] op_sel:[1,0,0] op_sel_hi:[1,1,1]
	v_add_f32_dpp v74, v74, v74 quad_perm:[2,3,0,1] row_mask:0xf bank_mask:0xf bound_ctrl:1
	v_pk_fma_f32 v[18:19], v[26:27], v[122:123], v[14:15] op_sel:[1,0,0] op_sel_hi:[1,1,1]
	v_pk_mul_f32 v[198:199], v[12:13], v[136:137]
	v_add_f32_dpp v74, v74, v74 row_half_mirror row_mask:0xf bank_mask:0xf bound_ctrl:1
	v_pk_fma_f32 v[198:199], v[14:15], v[138:139], v[198:199]
	v_add_f32_e32 v162, v198, v199
	v_add_f32_dpp v74, v74, v74 row_mirror row_mask:0xf bank_mask:0xf bound_ctrl:1
	v_pk_fma_f32 v[12:13], v[116:117], v[74:75], v[16:17] op_sel_hi:[1,0,1] neg_lo:[0,1,0] neg_hi:[0,1,0]
	v_pk_fma_f32 v[14:15], v[118:119], v[74:75], v[18:19] op_sel_hi:[1,0,1] neg_lo:[0,1,0] neg_hi:[0,1,0]
	v_add_f32_dpp v183, v159, v159 row_mirror row_mask:0xf bank_mask:0xc
	v_add_f32_dpp v187, v179, v179 row_half_mirror row_mask:0xf bank_mask:0x5
	s_waitcnt lgkmcnt(5)
; #define RW_LD(X, s) do { X.d = *(const LAS f32x4*)(bs + (s) * 256); X.k = *(const LAS f32x4*)(bs + 8192 + (s) * 256); X.a = *(const LAS f32x4*)(bs + 16384 + (s) * 256); \
;                          X.p = *(const LAS f32x4*)(bs + 24576 + (s) * 256); X.r = *(const LAS f32x4*)(bs + 32768 + (s) * 256); X.v = *(const LAS float*)(bv + (s) * 64); } while (0)
; #define RW_STEP(X, s) do { float sa = fmaf(S[3], X.k[3], fmaf(S[2], X.k[2], fmaf(S[1], X.k[1], S[0] * X.k[0]))); const f32x4 T = S * X.d + X.v * X.p; sa = -red16(sa); \
;                            S = T + sa * X.a; float y = fmaf(S[3], X.r[3], fmaf(S[2], X.r[2], fmaf(S[1], X.r[1], S[0] * X.r[0]))); y = red16(y); \
;                            yk = fmaf(selv[(s) & 15], y, yk); } while (0)
; #define RW_YST(s) do { if ((s) == 15) { ob[(size_t)(rowbase + c * 32 + seg) * D + 512 + h * 64 + vrow] = f2bf(yk); yk = 0.f; } } while (0)
; __device__ __forceinline__ void rwkv_scan(const Params& p, LAS unsigned char* lds, int rowbase, int T, int h, int q4, const float* S0, float* Sout) {
;     ...
;             RwStep xa, xb, xc; float yk = 0.f;
;     ...
;             RW_LD(xa, 0); RW_LD(xb, 1);
; #pragma unroll
;             for (int s = 0; s < 30; s += 3) {
;                 RW_LD(xc, s + 2); RW_STEP(xa, s); RW_YST(s);
;                 RW_LD(xa, s + 3); RW_STEP(xb, s + 1); RW_YST(s + 1);
;                 RW_LD(xb, s + 4); RW_STEP(xc, s + 2); RW_YST(s + 2);
;             }
	v_pk_mul_f32 v[72:73], v[12:13], v[76:77]
	v_add_f32_dpp v187, v183, v183 row_half_mirror row_mask:0xf bank_mask:0xa
	v_pk_fma_f32 v[72:73], v[14:15], v[78:79], v[72:73]
	ds_read_b128 v[112:115], v2 offset:5888
	v_add_f32_e32 v74, v72, v73
	ds_read_b128 v[120:123], v2 offset:22272
	ds_read_b128 v[116:119], v2 offset:14080
	v_add_f32_dpp v74, v74, v74 quad_perm:[1,0,3,2] row_mask:0xf bank_mask:0xf bound_ctrl:1
	ds_read_b128 v[136:139], v2 offset:30464
	v_pk_fma_f32 v[16:17], v[28:29], v[84:85], v[12:13] op_sel_hi:[0,1,1]
	v_add_f32_dpp v74, v74, v74 quad_perm:[2,3,0,1] row_mask:0xf bank_mask:0xf bound_ctrl:1
	v_pk_fma_f32 v[18:19], v[28:29], v[86:87], v[14:15] op_sel_hi:[0,1,1]
	v_pk_mul_f32 v[198:199], v[12:13], v[140:141]
	v_add_f32_dpp v74, v74, v74 row_half_mirror row_mask:0xf bank_mask:0xf bound_ctrl:1
	v_pk_fma_f32 v[198:199], v[14:15], v[142:143], v[198:199]
	v_add_f32_e32 v163, v198, v199
	v_add_f32_dpp v74, v74, v74 row_mirror row_mask:0xf bank_mask:0xf bound_ctrl:1
	v_pk_fma_f32 v[12:13], v[80:81], v[74:75], v[16:17] op_sel_hi:[1,0,1] neg_lo:[0,1,0] neg_hi:[0,1,0]
	v_pk_fma_f32 v[14:15], v[82:83], v[74:75], v[18:19] op_sel_hi:[1,0,1] neg_lo:[0,1,0] neg_hi:[0,1,0]
	v_cndmask_b32_e64 v190, v185, v187, s[98:99]
	v_cndmask_b32_e64 v191, v187, v185, s[98:99]
	v_pk_mul_f32 v[72:73], v[12:13], v[88:89]
	v_pk_fma_f32 v[72:73], v[14:15], v[90:91], v[72:73]
	v_add_f32_dpp v189, v191, v190 quad_perm:[2,3,0,1] row_mask:0xf bank_mask:0xf
	ds_read_b128 v[76:79], v2 offset:6144
	v_add_f32_e32 v74, v72, v73
	ds_read_b128 v[84:87], v2 offset:22528
	ds_read_b128 v[80:83], v2 offset:14336
	v_add_f32_dpp v74, v74, v74 quad_perm:[1,0,3,2] row_mask:0xf bank_mask:0xf bound_ctrl:1
	ds_read_b128 v[140:143], v2 offset:30720
	ds_read_b128 v[24:27], v3 offset:96
	v_add_f32_dpp v74, v74, v74 quad_perm:[2,3,0,1] row_mask:0xf bank_mask:0xf bound_ctrl:1
	v_pk_fma_f32 v[16:17], v[28:29], v[96:97], v[12:13] op_sel:[1,0,0] op_sel_hi:[1,1,1]
	v_pk_fma_f32 v[18:19], v[28:29], v[98:99], v[14:15] op_sel:[1,0,0] op_sel_hi:[1,1,1]
	v_add_f32_dpp v74, v74, v74 row_half_mirror row_mask:0xf bank_mask:0xf bound_ctrl:1
	v_pk_mul_f32 v[198:199], v[12:13], v[124:125]
	v_pk_fma_f32 v[198:199], v[14:15], v[126:127], v[198:199]
	v_add_f32_dpp v74, v74, v74 row_mirror row_mask:0xf bank_mask:0xf bound_ctrl:1
	v_add_f32_e32 v164, v198, v199
	v_pk_fma_f32 v[12:13], v[92:93], v[74:75], v[16:17] op_sel_hi:[1,0,1] neg_lo:[0,1,0] neg_hi:[0,1,0]
	v_pk_fma_f32 v[14:15], v[94:95], v[74:75], v[18:19] op_sel_hi:[1,0,1] neg_lo:[0,1,0] neg_hi:[0,1,0]
	v_cndmask_b32_e64 v190, v188, v189, s[100:101]
	v_cndmask_b32_e64 v191, v189, v188, s[100:101]
	s_waitcnt lgkmcnt(6)
	v_pk_mul_f32 v[72:73], v[12:13], v[100:101]
	v_add_f32_dpp v192, v191, v190 quad_perm:[1,0,3,2] row_mask:0xf bank_mask:0xf
	v_pk_fma_f32 v[72:73], v[14:15], v[102:103], v[72:73]
	ds_read_b128 v[88:91], v2 offset:6400
	v_add_f32_e32 v74, v72, v73
	ds_read_b128 v[96:99], v2 offset:22784
	ds_read_b128 v[92:95], v2 offset:14592
	v_add_f32_dpp v74, v74, v74 quad_perm:[1,0,3,2] row_mask:0xf bank_mask:0xf bound_ctrl:1
	ds_read_b128 v[124:127], v2 offset:30976
	v_pk_fma_f32 v[16:17], v[30:31], v[108:109], v[12:13] op_sel_hi:[0,1,1]
	v_add_f32_dpp v74, v74, v74 quad_perm:[2,3,0,1] row_mask:0xf bank_mask:0xf bound_ctrl:1
	v_pk_fma_f32 v[18:19], v[30:31], v[110:111], v[14:15] op_sel_hi:[0,1,1]
	v_pk_mul_f32 v[198:199], v[12:13], v[128:129]
	v_add_f32_dpp v74, v74, v74 row_half_mirror row_mask:0xf bank_mask:0xf bound_ctrl:1
	v_pk_fma_f32 v[198:199], v[14:15], v[130:131], v[198:199]
	v_add_f32_e32 v165, v198, v199
	v_add_f32_dpp v74, v74, v74 row_mirror row_mask:0xf bank_mask:0xf bound_ctrl:1
	v_pk_fma_f32 v[12:13], v[104:105], v[74:75], v[16:17] op_sel_hi:[1,0,1] neg_lo:[0,1,0] neg_hi:[0,1,0]
	v_pk_fma_f32 v[14:15], v[106:107], v[74:75], v[18:19] op_sel_hi:[1,0,1] neg_lo:[0,1,0] neg_hi:[0,1,0]
	v_lshlrev_b32_e32 v194, 11, v5
	v_mov_b32_e32 v195, 0
	v_pk_mul_f32 v[72:73], v[12:13], v[112:113]
	v_pk_fma_f32 v[72:73], v[14:15], v[114:115], v[72:73]
	ds_read_b128 v[100:103], v2 offset:6656
	v_add_f32_e32 v74, v72, v73
	ds_read_b128 v[108:111], v2 offset:23040
	ds_read_b128 v[104:107], v2 offset:14848
	v_add_f32_dpp v74, v74, v74 quad_perm:[1,0,3,2] row_mask:0xf bank_mask:0xf bound_ctrl:1
	ds_read_b128 v[128:131], v2 offset:31232
	v_pk_fma_f32 v[16:17], v[30:31], v[120:121], v[12:13] op_sel:[1,0,0] op_sel_hi:[1,1,1]
	v_add_f32_dpp v74, v74, v74 quad_perm:[2,3,0,1] row_mask:0xf bank_mask:0xf bound_ctrl:1
	v_pk_fma_f32 v[18:19], v[30:31], v[122:123], v[14:15] op_sel:[1,0,0] op_sel_hi:[1,1,1]
	v_pk_mul_f32 v[198:199], v[12:13], v[132:133]
	v_add_f32_dpp v74, v74, v74 row_half_mirror row_mask:0xf bank_mask:0xf bound_ctrl:1
	v_pk_fma_f32 v[198:199], v[14:15], v[134:135], v[198:199]
	v_add_f32_e32 v166, v198, v199
	v_add_f32_dpp v74, v74, v74 row_mirror row_mask:0xf bank_mask:0xf bound_ctrl:1
	v_pk_fma_f32 v[12:13], v[116:117], v[74:75], v[16:17] op_sel_hi:[1,0,1] neg_lo:[0,1,0] neg_hi:[0,1,0]
	v_pk_fma_f32 v[14:15], v[118:119], v[74:75], v[18:19] op_sel_hi:[1,0,1] neg_lo:[0,1,0] neg_hi:[0,1,0]
	v_cvt_pk_bf16_f32 v193, v192, v192
	v_lshl_add_u64 v[194:195], v[6:7], 0, v[194:195]
	s_waitcnt lgkmcnt(5)
; #define RW_LD(X, s) do { X.d = *(const LAS f32x4*)(bs + (s) * 256); X.k = *(const LAS f32x4*)(bs + 8192 + (s) * 256); X.a = *(const LAS f32x4*)(bs + 16384 + (s) * 256); \
;                          X.p = *(const LAS f32x4*)(bs + 24576 + (s) * 256); X.r = *(const LAS f32x4*)(bs + 32768 + (s) * 256); X.v = *(const LAS float*)(bv + (s) * 64); } while (0)
; #define RW_STEP(X, s) do { float sa = fmaf(S[3], X.k[3], fmaf(S[2], X.k[2], fmaf(S[1], X.k[1], S[0] * X.k[0]))); const f32x4 T = S * X.d + X.v * X.p; sa = -red16(sa); \
;                            S = T + sa * X.a; float y = fmaf(S[3], X.r[3], fmaf(S[2], X.r[2], fmaf(S[1], X.r[1], S[0] * X.r[0]))); y = red16(y); \
;                            yk = fmaf(selv[(s) & 15], y, yk); } while (0)
; #define RW_YST(s) do { if ((s) == 15) { ob[(size_t)(rowbase + c * 32 + seg) * D + 512 + h * 64 + vrow] = f2bf(yk); yk = 0.f; } } while (0)
; __device__ __forceinline__ void rwkv_scan(const Params& p, LAS unsigned char* lds, int rowbase, int T, int h, int q4, const float* S0, float* Sout) {
;     ...
;             RwStep xa, xb, xc; float yk = 0.f;
;     ...
;             RW_LD(xa, 0); RW_LD(xb, 1);
; #pragma unroll
;             for (int s = 0; s < 30; s += 3) {
;                 RW_LD(xc, s + 2); RW_STEP(xa, s); RW_YST(s);
;                 RW_LD(xa, s + 3); RW_STEP(xb, s + 1); RW_YST(s + 1);
;                 RW_LD(xb, s + 4); RW_STEP(xc, s + 2); RW_YST(s + 2);
;             }
	v_pk_mul_f32 v[72:73], v[12:13], v[76:77]
	v_pk_fma_f32 v[72:73], v[14:15], v[78:79], v[72:73]
	ds_read_b128 v[112:115], v2 offset:6912
	v_add_f32_e32 v74, v72, v73
	ds_read_b128 v[120:123], v2 offset:23296
	ds_read_b128 v[116:119], v2 offset:15104
	v_add_f32_dpp v74, v74, v74 quad_perm:[1,0,3,2] row_mask:0xf bank_mask:0xf bound_ctrl:1
	ds_read_b128 v[132:135], v2 offset:31488
	v_pk_fma_f32 v[16:17], v[24:25], v[84:85], v[12:13] op_sel_hi:[0,1,1]
	v_add_f32_dpp v74, v74, v74 quad_perm:[2,3,0,1] row_mask:0xf bank_mask:0xf bound_ctrl:1
	v_pk_fma_f32 v[18:19], v[24:25], v[86:87], v[14:15] op_sel_hi:[0,1,1]
	v_pk_mul_f32 v[198:199], v[12:13], v[136:137]
	v_add_f32_dpp v74, v74, v74 row_half_mirror row_mask:0xf bank_mask:0xf bound_ctrl:1
	v_pk_fma_f32 v[198:199], v[14:15], v[138:139], v[198:199]
	v_add_f32_e32 v167, v198, v199
	v_add_f32_dpp v74, v74, v74 row_mirror row_mask:0xf bank_mask:0xf bound_ctrl:1
	v_pk_fma_f32 v[12:13], v[80:81], v[74:75], v[16:17] op_sel_hi:[1,0,1] neg_lo:[0,1,0] neg_hi:[0,1,0]
	v_pk_fma_f32 v[14:15], v[82:83], v[74:75], v[18:19] op_sel_hi:[1,0,1] neg_lo:[0,1,0] neg_hi:[0,1,0]
	global_store_short v[194:195], v193, off offset:1024
	v_pk_mul_f32 v[72:73], v[12:13], v[88:89]
	v_pk_fma_f32 v[72:73], v[14:15], v[90:91], v[72:73]
	ds_read_b128 v[76:79], v2 offset:7168
	v_add_f32_e32 v74, v72, v73
	ds_read_b128 v[84:87], v2 offset:23552
	ds_read_b128 v[80:83], v2 offset:15360
	v_add_f32_dpp v74, v74, v74 quad_perm:[1,0,3,2] row_mask:0xf bank_mask:0xf bound_ctrl:1
	ds_read_b128 v[136:139], v2 offset:31744
	ds_read_b128 v[28:31], v3 offset:112
	v_add_f32_dpp v74, v74, v74 quad_perm:[2,3,0,1] row_mask:0xf bank_mask:0xf bound_ctrl:1
	v_pk_fma_f32 v[16:17], v[24:25], v[96:97], v[12:13] op_sel:[1,0,0] op_sel_hi:[1,1,1]
	v_pk_fma_f32 v[18:19], v[24:25], v[98:99], v[14:15] op_sel:[1,0,0] op_sel_hi:[1,1,1]
	v_add_f32_dpp v74, v74, v74 row_half_mirror row_mask:0xf bank_mask:0xf bound_ctrl:1
	v_pk_mul_f32 v[198:199], v[12:13], v[140:141]
	v_pk_fma_f32 v[198:199], v[14:15], v[142:143], v[198:199]
	v_add_f32_dpp v74, v74, v74 row_mirror row_mask:0xf bank_mask:0xf bound_ctrl:1
	v_add_f32_e32 v168, v198, v199
	v_pk_fma_f32 v[12:13], v[92:93], v[74:75], v[16:17] op_sel_hi:[1,0,1] neg_lo:[0,1,0] neg_hi:[0,1,0]
	v_pk_fma_f32 v[14:15], v[94:95], v[74:75], v[18:19] op_sel_hi:[1,0,1] neg_lo:[0,1,0] neg_hi:[0,1,0]
	v_add_f32_dpp v176, v160, v160 row_mirror row_mask:0xf bank_mask:0x3
	s_waitcnt lgkmcnt(6)
	v_pk_mul_f32 v[72:73], v[12:13], v[100:101]
	v_add_f32_dpp v176, v168, v168 row_mirror row_mask:0xf bank_mask:0xc
	v_pk_fma_f32 v[72:73], v[14:15], v[102:103], v[72:73]
	ds_read_b128 v[88:91], v2 offset:7424
	v_add_f32_e32 v74, v72, v73
	ds_read_b128 v[96:99], v2 offset:23808
	ds_read_b128 v[92:95], v2 offset:15616
	v_add_f32_dpp v74, v74, v74 quad_perm:[1,0,3,2] row_mask:0xf bank_mask:0xf bound_ctrl:1
	ds_read_b128 v[140:143], v2 offset:32000
	v_pk_fma_f32 v[16:17], v[26:27], v[108:109], v[12:13] op_sel_hi:[0,1,1]
	v_add_f32_dpp v74, v74, v74 quad_perm:[2,3,0,1] row_mask:0xf bank_mask:0xf bound_ctrl:1
	v_pk_fma_f32 v[18:19], v[26:27], v[110:111], v[14:15] op_sel_hi:[0,1,1]
	v_pk_mul_f32 v[198:199], v[12:13], v[124:125]
	v_add_f32_dpp v74, v74, v74 row_half_mirror row_mask:0xf bank_mask:0xf bound_ctrl:1
	v_pk_fma_f32 v[198:199], v[14:15], v[126:127], v[198:199]
	v_add_f32_e32 v169, v198, v199
	v_add_f32_dpp v74, v74, v74 row_mirror row_mask:0xf bank_mask:0xf bound_ctrl:1
	v_pk_fma_f32 v[12:13], v[104:105], v[74:75], v[16:17] op_sel_hi:[1,0,1] neg_lo:[0,1,0] neg_hi:[0,1,0]
	v_pk_fma_f32 v[14:15], v[106:107], v[74:75], v[18:19] op_sel_hi:[1,0,1] neg_lo:[0,1,0] neg_hi:[0,1,0]
	v_add_f32_dpp v177, v161, v161 row_mirror row_mask:0xf bank_mask:0x3
	v_pk_mul_f32 v[72:73], v[12:13], v[112:113]
	v_pk_fma_f32 v[72:73], v[14:15], v[114:115], v[72:73]
	v_add_f32_dpp v177, v169, v169 row_mirror row_mask:0xf bank_mask:0xc
	ds_read_b128 v[100:103], v2 offset:7680
	v_add_f32_e32 v74, v72, v73
	ds_read_b128 v[108:111], v2 offset:24064
	ds_read_b128 v[104:107], v2 offset:15872
	v_add_f32_dpp v74, v74, v74 quad_perm:[1,0,3,2] row_mask:0xf bank_mask:0xf bound_ctrl:1
	ds_read_b128 v[124:127], v2 offset:32256
	v_pk_fma_f32 v[16:17], v[26:27], v[120:121], v[12:13] op_sel:[1,0,0] op_sel_hi:[1,1,1]
	v_add_f32_dpp v74, v74, v74 quad_perm:[2,3,0,1] row_mask:0xf bank_mask:0xf bound_ctrl:1
	v_pk_fma_f32 v[18:19], v[26:27], v[122:123], v[14:15] op_sel:[1,0,0] op_sel_hi:[1,1,1]
	v_pk_mul_f32 v[198:199], v[12:13], v[128:129]
	v_add_f32_dpp v74, v74, v74 row_half_mirror row_mask:0xf bank_mask:0xf bound_ctrl:1
	v_pk_fma_f32 v[198:199], v[14:15], v[130:131], v[198:199]
	v_add_f32_e32 v170, v198, v199
	v_add_f32_dpp v74, v74, v74 row_mirror row_mask:0xf bank_mask:0xf bound_ctrl:1
	v_pk_fma_f32 v[12:13], v[116:117], v[74:75], v[16:17] op_sel_hi:[1,0,1] neg_lo:[0,1,0] neg_hi:[0,1,0]
	v_pk_fma_f32 v[14:15], v[118:119], v[74:75], v[18:19] op_sel_hi:[1,0,1] neg_lo:[0,1,0] neg_hi:[0,1,0]
	v_add_f32_dpp v178, v162, v162 row_mirror row_mask:0xf bank_mask:0x3
	s_waitcnt lgkmcnt(5)
; __device__ __forceinline__ bf16_t f2bf(float f) { return (bf16_t)(cvt_pk_bf16(f, 0.f) & 0xffffu); }
; #define RW_LD(X, s) do { X.d = *(const LAS f32x4*)(bs + (s) * 256); X.k = *(const LAS f32x4*)(bs + 8192 + (s) * 256); X.a = *(const LAS f32x4*)(bs + 16384 + (s) * 256); \
;                          X.p = *(const LAS f32x4*)(bs + 24576 + (s) * 256); X.r = *(const LAS f32x4*)(bs + 32768 + (s) * 256); X.v = *(const LAS float*)(bv + (s) * 64); } while (0)
; #define RW_STEP(X, s) do { float sa = fmaf(S[3], X.k[3], fmaf(S[2], X.k[2], fmaf(S[1], X.k[1], S[0] * X.k[0]))); const f32x4 T = S * X.d + X.v * X.p; sa = -red16(sa); \
;                            S = T + sa * X.a; float y = fmaf(S[3], X.r[3], fmaf(S[2], X.r[2], fmaf(S[1], X.r[1], S[0] * X.r[0]))); y = red16(y); \
;                            yk = fmaf(selv[(s) & 15], y, yk); } while (0)
; #define RW_YST(s) do { if ((s) == 15) { ob[(size_t)(rowbase + c * 32 + seg) * D + 512 + h * 64 + vrow] = f2bf(yk); yk = 0.f; } } while (0)
; __device__ __forceinline__ void rwkv_scan(const Params& p, LAS unsigned char* lds, int rowbase, int T, int h, int q4, const float* S0, float* Sout) {
;     ...
;             RwStep xa, xb, xc; float yk = 0.f;
;     ...
;             RW_LD(xa, 0); RW_LD(xb, 1);
; #pragma unroll
;             for (int s = 0; s < 30; s += 3) {
;                 RW_LD(xc, s + 2); RW_STEP(xa, s); RW_YST(s);
;                 RW_LD(xa, s + 3); RW_STEP(xb, s + 1); RW_YST(s + 1);
;                 RW_LD(xb, s + 4); RW_STEP(xc, s + 2); RW_YST(s + 2);
;             }
;             RW_STEP(xa, 30); RW_STEP(xb, 31);
;             ob[(size_t)(rowbase + c * 32 + 16 + seg) * D + 512 + h * 64 + vrow] = f2bf(yk);
;     ...
;         }
;     }
;     if (comp) *(f32x4*)(Sout + vrow * 64 + seg * 4) = S;
	v_pk_mul_f32 v[72:73], v[12:13], v[76:77]
	v_add_f32_dpp v178, v170, v170 row_mirror row_mask:0xf bank_mask:0xc
	v_pk_fma_f32 v[72:73], v[14:15], v[78:79], v[72:73]
	ds_read_b128 v[112:115], v2 offset:7936
	v_add_f32_e32 v74, v72, v73
	ds_read_b128 v[120:123], v2 offset:24320
	ds_read_b128 v[116:119], v2 offset:16128
	v_add_f32_dpp v74, v74, v74 quad_perm:[1,0,3,2] row_mask:0xf bank_mask:0xf bound_ctrl:1
	ds_read_b128 v[128:131], v2 offset:32512
	v_pk_fma_f32 v[16:17], v[28:29], v[84:85], v[12:13] op_sel_hi:[0,1,1]
	v_add_f32_dpp v74, v74, v74 quad_perm:[2,3,0,1] row_mask:0xf bank_mask:0xf bound_ctrl:1
	v_pk_fma_f32 v[18:19], v[28:29], v[86:87], v[14:15] op_sel_hi:[0,1,1]
	v_pk_mul_f32 v[198:199], v[12:13], v[132:133]
	v_add_f32_dpp v74, v74, v74 row_half_mirror row_mask:0xf bank_mask:0xf bound_ctrl:1
	v_pk_fma_f32 v[198:199], v[14:15], v[134:135], v[198:199]
	v_add_f32_e32 v171, v198, v199
	v_add_f32_dpp v74, v74, v74 row_mirror row_mask:0xf bank_mask:0xf bound_ctrl:1
	v_pk_fma_f32 v[12:13], v[80:81], v[74:75], v[16:17] op_sel_hi:[1,0,1] neg_lo:[0,1,0] neg_hi:[0,1,0]
	v_pk_fma_f32 v[14:15], v[82:83], v[74:75], v[18:19] op_sel_hi:[1,0,1] neg_lo:[0,1,0] neg_hi:[0,1,0]
	v_add_f32_dpp v179, v163, v163 row_mirror row_mask:0xf bank_mask:0x3
	v_pk_mul_f32 v[72:73], v[12:13], v[88:89]
	v_pk_fma_f32 v[72:73], v[14:15], v[90:91], v[72:73]
	v_add_f32_dpp v179, v171, v171 row_mirror row_mask:0xf bank_mask:0xc
	v_pk_fma_f32 v[16:17], v[28:29], v[96:97], v[12:13] op_sel:[1,0,0] op_sel_hi:[1,1,1]
	v_add_f32_e32 v74, v72, v73
	v_pk_fma_f32 v[18:19], v[28:29], v[98:99], v[14:15] op_sel:[1,0,0] op_sel_hi:[1,1,1]
	v_pk_mul_f32 v[198:199], v[12:13], v[136:137]
	v_add_f32_dpp v74, v74, v74 quad_perm:[1,0,3,2] row_mask:0xf bank_mask:0xf bound_ctrl:1
	v_pk_fma_f32 v[198:199], v[14:15], v[138:139], v[198:199]
	v_add_f32_e32 v172, v198, v199
	v_add_f32_dpp v74, v74, v74 quad_perm:[2,3,0,1] row_mask:0xf bank_mask:0xf bound_ctrl:1
	v_add_f32_dpp v180, v164, v164 row_mirror row_mask:0xf bank_mask:0x3
	s_nop 1
	v_add_f32_dpp v180, v172, v172 row_mirror row_mask:0xf bank_mask:0xc
	v_add_f32_dpp v74, v74, v74 row_half_mirror row_mask:0xf bank_mask:0xf bound_ctrl:1
	s_nop 1
	v_add_f32_dpp v74, v74, v74 row_mirror row_mask:0xf bank_mask:0xf bound_ctrl:1
	v_pk_fma_f32 v[12:13], v[92:93], v[74:75], v[16:17] op_sel_hi:[1,0,1] neg_lo:[0,1,0] neg_hi:[0,1,0]
	v_pk_fma_f32 v[14:15], v[94:95], v[74:75], v[18:19] op_sel_hi:[1,0,1] neg_lo:[0,1,0] neg_hi:[0,1,0]
	s_waitcnt lgkmcnt(0)
	v_pk_mul_f32 v[72:73], v[12:13], v[100:101]
	v_pk_fma_f32 v[72:73], v[14:15], v[102:103], v[72:73]
	v_pk_fma_f32 v[16:17], v[30:31], v[108:109], v[12:13] op_sel_hi:[0,1,1]
	v_add_f32_e32 v74, v72, v73
	v_pk_fma_f32 v[18:19], v[30:31], v[110:111], v[14:15] op_sel_hi:[0,1,1]
	v_pk_mul_f32 v[198:199], v[12:13], v[140:141]
	v_add_f32_dpp v74, v74, v74 quad_perm:[1,0,3,2] row_mask:0xf bank_mask:0xf bound_ctrl:1
	v_pk_fma_f32 v[198:199], v[14:15], v[142:143], v[198:199]
	v_add_f32_e32 v173, v198, v199
	v_add_f32_dpp v74, v74, v74 quad_perm:[2,3,0,1] row_mask:0xf bank_mask:0xf bound_ctrl:1
	v_add_f32_dpp v184, v176, v176 row_half_mirror row_mask:0xf bank_mask:0x5
	s_nop 1
	v_add_f32_dpp v184, v180, v180 row_half_mirror row_mask:0xf bank_mask:0xa
	v_add_f32_dpp v74, v74, v74 row_half_mirror row_mask:0xf bank_mask:0xf bound_ctrl:1
	s_nop 1
	v_add_f32_dpp v74, v74, v74 row_mirror row_mask:0xf bank_mask:0xf bound_ctrl:1
	v_pk_fma_f32 v[12:13], v[104:105], v[74:75], v[16:17] op_sel_hi:[1,0,1] neg_lo:[0,1,0] neg_hi:[0,1,0]
	v_pk_fma_f32 v[14:15], v[106:107], v[74:75], v[18:19] op_sel_hi:[1,0,1] neg_lo:[0,1,0] neg_hi:[0,1,0]
	v_pk_mul_f32 v[72:73], v[12:13], v[112:113]
	v_pk_fma_f32 v[72:73], v[14:15], v[114:115], v[72:73]
	v_pk_fma_f32 v[16:17], v[30:31], v[120:121], v[12:13] op_sel:[1,0,0] op_sel_hi:[1,1,1]
	v_add_f32_e32 v74, v72, v73
	v_pk_fma_f32 v[18:19], v[30:31], v[122:123], v[14:15] op_sel:[1,0,0] op_sel_hi:[1,1,1]
	v_pk_mul_f32 v[198:199], v[12:13], v[124:125]
	v_add_f32_dpp v74, v74, v74 quad_perm:[1,0,3,2] row_mask:0xf bank_mask:0xf bound_ctrl:1
	v_pk_fma_f32 v[198:199], v[14:15], v[126:127], v[198:199]
	v_add_f32_e32 v174, v198, v199
	v_add_f32_dpp v74, v74, v74 quad_perm:[2,3,0,1] row_mask:0xf bank_mask:0xf bound_ctrl:1
	v_add_f32_dpp v181, v165, v165 row_mirror row_mask:0xf bank_mask:0x3
	v_add_f32_dpp v185, v177, v177 row_half_mirror row_mask:0xf bank_mask:0x5
	v_add_f32_dpp v74, v74, v74 row_half_mirror row_mask:0xf bank_mask:0xf bound_ctrl:1
	v_add_f32_dpp v181, v173, v173 row_mirror row_mask:0xf bank_mask:0xc
	s_nop 0
	v_add_f32_dpp v74, v74, v74 row_mirror row_mask:0xf bank_mask:0xf bound_ctrl:1
	v_pk_fma_f32 v[12:13], v[116:117], v[74:75], v[16:17] op_sel_hi:[1,0,1] neg_lo:[0,1,0] neg_hi:[0,1,0]
	v_pk_fma_f32 v[14:15], v[118:119], v[74:75], v[18:19] op_sel_hi:[1,0,1] neg_lo:[0,1,0] neg_hi:[0,1,0]
	ds_read_b128 v[20:23], v4
	v_pk_mul_f32 v[198:199], v[12:13], v[128:129]
	v_pk_fma_f32 v[198:199], v[14:15], v[130:131], v[198:199]
	v_add_f32_e32 v175, v198, v199
	v_add_f32_dpp v185, v181, v181 row_half_mirror row_mask:0xf bank_mask:0xa
	v_add_f32_dpp v182, v166, v166 row_mirror row_mask:0xf bank_mask:0x3
	s_nop 1
	v_add_f32_dpp v182, v174, v174 row_mirror row_mask:0xf bank_mask:0xc
	v_add_f32_dpp v186, v178, v178 row_half_mirror row_mask:0xf bank_mask:0x5
	s_nop 1
	v_add_f32_dpp v186, v182, v182 row_half_mirror row_mask:0xf bank_mask:0xa
	v_cndmask_b32_e64 v190, v184, v186, s[98:99]
	v_cndmask_b32_e64 v191, v186, v184, s[98:99]
	v_add_f32_dpp v183, v167, v167 row_mirror row_mask:0xf bank_mask:0x3
	v_add_f32_dpp v187, v179, v179 row_half_mirror row_mask:0xf bank_mask:0x5
	v_add_f32_dpp v188, v191, v190 quad_perm:[2,3,0,1] row_mask:0xf bank_mask:0xf
	s_waitcnt lgkmcnt(0)
	v_add_f32_dpp v183, v175, v175 row_mirror row_mask:0xf bank_mask:0xc
	v_pk_mul_f32 v[12:13], v[12:13], v[20:21]
	v_pk_mul_f32 v[14:15], v[14:15], v[22:23]
	v_add_f32_dpp v187, v183, v183 row_half_mirror row_mask:0xf bank_mask:0xa
	v_cndmask_b32_e64 v190, v185, v187, s[98:99]
	v_cndmask_b32_e64 v191, v187, v185, s[98:99]
	s_nop 1
	v_add_f32_dpp v189, v191, v190 quad_perm:[2,3,0,1] row_mask:0xf bank_mask:0xf
	v_cndmask_b32_e64 v190, v188, v189, s[100:101]
	v_cndmask_b32_e64 v191, v189, v188, s[100:101]
	v_add_u32_e32 v196, 16, v5
	v_lshlrev_b32_e32 v194, 11, v196
	v_add_f32_dpp v192, v191, v190 quad_perm:[1,0,3,2] row_mask:0xf bank_mask:0xf
	v_mov_b32_e32 v195, 0
	v_cvt_pk_bf16_f32 v193, v192, v192
	v_lshl_add_u64 v[194:195], v[6:7], 0, v[194:195]
	global_store_short v[194:195], v193, off offset:1024
	v_add_u32_e32 v5, 32, v5
	s_bitcmp1_b32 s22, 0
	s_cselect_b32 s4, s39, s38
	v_add_u32_e32 v2, s4, v2
	v_add_u32_e32 v3, s4, v3
	v_add_u32_e32 v4, s4, v4
	s_add_i32 s22, s22, 1
	s_cmpk_lt_i32 s22, 128
	s_cbranch_scc1 .Lrw3_cloop
	global_store_dwordx4 v[8:9], v[12:15], off
	s_branch .LBB0_738
